# stack + W_o prologue: residual-tile unpack overlaps the last operand DMAs (vmcnt(0) moved behind the unpack)
# baseline (speedup 1.0000x reference)
; __device__ __forceinline__ void unpack8(u32x4 g, f32x4& a, f32x4& b) { a = (f32x4){bf_lo(g.x), bf_hi(g.x), bf_lo(g.y), bf_hi(g.y)}; b = (f32x4){bf_lo(g.z), bf_hi(g.z), bf_lo(g.w), bf_hi(g.w)}; }
; #define PG8_STAGE(bufoff, gbase, voff) do { _Pragma("unroll") for (int _i = 0; _i < 2; ++_i) \
;         __builtin_amdgcn_global_load_lds((const unsigned*)((const char*)(gbase) + (voff)[_i]), (LAS unsigned*)(lds + (bufoff) + ldsw + _i * 8192), 16, 0, 0); } while (0)
; #define PG8_WAIT_V(n) asm volatile("s_waitcnt vmcnt(" #n ")" ::: "memory")
; #define PG8_BAR __builtin_amdgcn_s_barrier()
; template <class Epi, class Order = StaticOrder, bool HALFN = false>
; __device__ __forceinline__ void gemm_phase(LAS unsigned char* lds, const Gemm g, const Epi& E) {
;     ...
;     PG8_STAGE(PG8_SB(0, 0), cB, voffB); PG8_STAGE(PG8_SB(0, 1), cB + hstepB, voffB); PG8_STAGE(PG8_SA(0, 0), cA, voffA); PG8_STAGE(PG8_SA(0, 1), cA + hstepA, voffA);
;     if (wr == 1) PG8_BAR;
;     PG8_WAIT_V(2); PG8_BAR;
;     PG8_STAGE(PG8_SB(1, 0), cB + kstep, voffB); PG8_STAGE(PG8_SA(1, 0), cA + kstep, voffA); PG8_STAGE(PG8_SB(1, 1), cB + hstepB + kstep, voffB);
;     PG8_WAIT_V(6); PG8_BAR;
;     __device__ __forceinline__ void init(f32x4 (&acc)[2][2][4][2], const Unit& u, int wr, int wc, int fr, int fq) const {
;     ...
;         } else {
;             EPI_ROWS_BEGIN EPI_COLS_BEGIN
;                 unpack8(*(const u32x4*)(baseb + (size_t)row * DM + col), acc[ai][bj][m][0], acc[ai][bj][m][1]);
;             EPI_END EPI_END
.LBB0_694:
	v_mov_b32_e32 v133, v0
	v_lshl_add_u64 v[82:83], s[80:81], 0, v[132:133]
	v_mov_b32_e32 v137, v0
	v_lshl_add_u64 v[84:85], s[80:81], 0, v[136:137]
	v_mov_b32_e32 v131, v0
	s_add_i32 m0, s16, 0x18000
	v_lshl_add_u64 v[82:83], v[82:83], 0, s[60:61]
	v_lshl_add_u64 v[102:103], s[62:63], 0, v[130:131]
	v_mov_b32_e32 v135, v0
	s_lshl_b32 s6, s4, 13
	s_lshl_b32 s7, s15, 7
	s_waitcnt vmcnt(2)
	s_barrier
	global_load_lds_dwordx4 v[82:83], off
	v_lshl_add_u64 v[82:83], v[84:85], 0, s[60:61]
	s_add_i32 m0, s16, 0x1a000
	s_add_i32 s20, s16, 0x8000
	s_add_i32 s21, s16, 0xa000
	v_lshl_add_u64 v[104:105], s[62:63], 0, v[134:135]
	global_load_lds_dwordx4 v[82:83], off
	v_lshl_add_u64 v[82:83], v[102:103], 0, s[60:61]
	s_mov_b32 m0, s20
	s_add_u32 s4, s80, 0x80080
	global_load_lds_dwordx4 v[82:83], off
	v_lshl_add_u64 v[82:83], v[104:105], 0, s[60:61]
	s_mov_b32 m0, s21
	s_addc_u32 s5, s81, 0
	global_load_lds_dwordx4 v[82:83], off
	s_add_i32 m0, s16, 0x1c000
	v_lshl_add_u64 v[82:83], s[4:5], 0, v[132:133]
	global_load_lds_dwordx4 v[82:83], off
	v_lshl_add_u64 v[82:83], s[4:5], 0, v[136:137]
	s_add_i32 m0, s16, 0x1e000
	v_or_b32_e32 v143, s11, v1
	global_load_lds_dwordx4 v[82:83], off
	v_lshlrev_b32_e32 v146, 4, v142
	v_lshlrev_b32_e32 v147, 6, v143
	s_movk_i32 s4, 0x3c0
	v_lshlrev_b32_e32 v143, 2, v143
	v_and_or_b32 v147, v147, s4, v146
	v_and_b32_e32 v143, 32, v143
	v_bitop3_b32 v147, v147, s6, v143 bitop3:0xde
	v_lshl_or_b32 v143, v1, 6, v146
	v_lshlrev_b32_e32 v146, 2, v1
	v_and_b32_e32 v146, 32, v146
	v_bitop3_b32 v143, v143, s7, v146 bitop3:0xde
	v_lshlrev_b32_e32 v146, 15, v138
	v_and_b32_e32 v146, 0xffff0000, v146
	v_lshl_add_u32 v139, v139, 12, v146
	v_and_b32_e32 v138, 1, v138
	v_lshl_or_b32 v138, v138, 6, v139
	v_lshl_add_u32 v138, v140, 1, v138
	v_lshlrev_b32_e32 v140, 15, v141
	v_and_b32_e32 v140, 0xffff0000, v140
	s_waitcnt vmcnt(6)
	v_lshl_add_u32 v140, v144, 12, v140
	v_and_b32_e32 v141, 1, v141
	s_cmpk_lt_u32 s22, 0x100
	v_lshl_or_b32 v140, v141, 6, v140
	v_lshlrev_b32_e32 v2, 16, v6
	v_and_b32_e32 v3, 0xffff0000, v6
	v_lshlrev_b32_e32 v4, 16, v7
	v_and_b32_e32 v5, 0xffff0000, v7
	v_lshlrev_b32_e32 v6, 16, v8
	v_and_b32_e32 v7, 0xffff0000, v8
	v_lshlrev_b32_e32 v8, 16, v9
	v_and_b32_e32 v9, 0xffff0000, v9
	v_lshlrev_b32_e32 v22, 16, v10
	v_and_b32_e32 v23, 0xffff0000, v10
	v_lshlrev_b32_e32 v24, 16, v11
	v_and_b32_e32 v25, 0xffff0000, v11
	v_lshlrev_b32_e32 v34, 16, v12
	v_and_b32_e32 v35, 0xffff0000, v12
	v_lshlrev_b32_e32 v36, 16, v13
	v_and_b32_e32 v37, 0xffff0000, v13
	v_lshlrev_b32_e32 v10, 16, v14
	v_and_b32_e32 v11, 0xffff0000, v14
	v_lshlrev_b32_e32 v12, 16, v15
	v_and_b32_e32 v13, 0xffff0000, v15
	v_lshlrev_b32_e32 v14, 16, v16
	v_and_b32_e32 v15, 0xffff0000, v16
	v_lshlrev_b32_e32 v16, 16, v17
	v_and_b32_e32 v17, 0xffff0000, v17
	v_lshlrev_b32_e32 v38, 16, v18
	v_and_b32_e32 v39, 0xffff0000, v18
	v_lshlrev_b32_e32 v40, 16, v19
	v_and_b32_e32 v41, 0xffff0000, v19
	v_lshlrev_b32_e32 v46, 16, v20
	v_and_b32_e32 v47, 0xffff0000, v20
	v_lshlrev_b32_e32 v48, 16, v21
	v_and_b32_e32 v49, 0xffff0000, v21
	v_lshlrev_b32_e32 v18, 16, v26
	v_and_b32_e32 v19, 0xffff0000, v26
	v_lshlrev_b32_e32 v20, 16, v27
	v_and_b32_e32 v21, 0xffff0000, v27
	v_lshlrev_b32_e32 v26, 16, v28
	v_and_b32_e32 v27, 0xffff0000, v28
	v_lshlrev_b32_e32 v28, 16, v29
	v_and_b32_e32 v29, 0xffff0000, v29
	v_lshlrev_b32_e32 v50, 16, v30
	v_and_b32_e32 v51, 0xffff0000, v30
	v_lshlrev_b32_e32 v52, 16, v31
	v_and_b32_e32 v53, 0xffff0000, v31
	v_lshlrev_b32_e32 v54, 16, v32
	v_and_b32_e32 v55, 0xffff0000, v32
	v_lshlrev_b32_e32 v56, 16, v33
	v_and_b32_e32 v57, 0xffff0000, v33
	v_lshlrev_b32_e32 v30, 16, v42
	v_and_b32_e32 v31, 0xffff0000, v42
	v_lshlrev_b32_e32 v32, 16, v43
	v_and_b32_e32 v33, 0xffff0000, v43
	v_lshlrev_b32_e32 v42, 16, v44
	v_and_b32_e32 v43, 0xffff0000, v44
	v_lshlrev_b32_e32 v44, 16, v45
	v_and_b32_e32 v45, 0xffff0000, v45
	v_lshlrev_b32_e32 v58, 16, v60
	v_and_b32_e32 v59, 0xffff0000, v60
	v_lshlrev_b32_e32 v60, 16, v61
	v_and_b32_e32 v61, 0xffff0000, v61
	v_lshlrev_b32_e32 v66, 16, v62
	v_and_b32_e32 v67, 0xffff0000, v62
	v_lshlrev_b32_e32 v68, 16, v63
	v_and_b32_e32 v69, 0xffff0000, v63
	v_lshlrev_b32_e32 v62, 16, v70
	v_and_b32_e32 v63, 0xffff0000, v70
	v_lshlrev_b32_e32 v64, 16, v71
	v_and_b32_e32 v65, 0xffff0000, v71
	v_lshlrev_b32_e32 v70, 16, v72
	v_and_b32_e32 v71, 0xffff0000, v72
	v_lshlrev_b32_e32 v72, 16, v73
	v_and_b32_e32 v73, 0xffff0000, v73
	v_lshlrev_b32_e32 v74, 16, v78
	v_and_b32_e32 v75, 0xffff0000, v78
	v_lshlrev_b32_e32 v76, 16, v79
	v_and_b32_e32 v77, 0xffff0000, v79
	v_lshlrev_b32_e32 v78, 16, v80
	v_and_b32_e32 v79, 0xffff0000, v80
	v_lshlrev_b32_e32 v80, 16, v81
	v_and_b32_e32 v81, 0xffff0000, v81
	v_lshlrev_b32_e32 v82, 16, v86
	v_and_b32_e32 v83, 0xffff0000, v86
	v_lshlrev_b32_e32 v84, 16, v87
	v_and_b32_e32 v85, 0xffff0000, v87
	v_lshlrev_b32_e32 v86, 16, v88
	v_and_b32_e32 v87, 0xffff0000, v88
	v_lshlrev_b32_e32 v88, 16, v89
	v_and_b32_e32 v89, 0xffff0000, v89
	v_lshlrev_b32_e32 v102, 16, v90
	v_and_b32_e32 v103, 0xffff0000, v90
	v_lshlrev_b32_e32 v104, 16, v91
	v_and_b32_e32 v105, 0xffff0000, v91
	v_lshlrev_b32_e32 v110, 16, v92
	v_and_b32_e32 v111, 0xffff0000, v92
	v_lshlrev_b32_e32 v112, 16, v93
	v_and_b32_e32 v113, 0xffff0000, v93
	v_lshlrev_b32_e32 v90, 16, v94
	v_and_b32_e32 v91, 0xffff0000, v94
	v_lshlrev_b32_e32 v92, 16, v95
	v_and_b32_e32 v93, 0xffff0000, v95
	v_lshlrev_b32_e32 v94, 16, v96
	v_and_b32_e32 v95, 0xffff0000, v96
	v_lshlrev_b32_e32 v96, 16, v97
	v_and_b32_e32 v97, 0xffff0000, v97
	v_lshlrev_b32_e32 v114, 16, v98
	v_and_b32_e32 v115, 0xffff0000, v98
	v_lshlrev_b32_e32 v116, 16, v99
	v_and_b32_e32 v117, 0xffff0000, v99
	v_lshlrev_b32_e32 v118, 16, v100
	v_and_b32_e32 v119, 0xffff0000, v100
	v_lshlrev_b32_e32 v120, 16, v101
	v_and_b32_e32 v121, 0xffff0000, v101
	v_lshlrev_b32_e32 v98, 16, v106
	v_and_b32_e32 v99, 0xffff0000, v106
	v_lshlrev_b32_e32 v100, 16, v107
	v_and_b32_e32 v101, 0xffff0000, v107
	v_lshlrev_b32_e32 v106, 16, v108
	v_and_b32_e32 v107, 0xffff0000, v108
	v_lshlrev_b32_e32 v108, 16, v109
	v_and_b32_e32 v109, 0xffff0000, v109
	v_lshlrev_b32_e32 v122, 16, v126
	v_and_b32_e32 v123, 0xffff0000, v126
	v_lshlrev_b32_e32 v124, 16, v127
	v_and_b32_e32 v125, 0xffff0000, v127
	v_lshlrev_b32_e32 v126, 16, v128
	v_and_b32_e32 v127, 0xffff0000, v128
	v_lshlrev_b32_e32 v128, 16, v129
	v_and_b32_e32 v129, 0xffff0000, v129
	s_cselect_b64 s[44:45], -1, 0
	v_mov_b32_e32 v139, v0
	v_lshl_add_u32 v140, v145, 1, v140
	v_mov_b32_e32 v141, v0
	s_mov_b32 s22, 0
	v_add_u32_e32 v144, 0, v147
	s_waitcnt vmcnt(0)
	s_barrier
	s_branch .LBB0_697
